# MLA loop: two barriers per tile with waves 4-7 one barrier behind (K staged before barrier 1, V before barrier 2), plus index-add and row-sum trims
# speedup vs baseline: 1.0028x; 1.0028x over previous
; __device__ __forceinline__ int hw_lane_id() { return (int)__builtin_amdgcn_mbcnt_hi(~0u, __builtin_amdgcn_mbcnt_lo(~0u, 0u)); }
; #define LAS __attribute__((address_space(3)))
; __device__ __forceinline__ void mla_unit2(LAS unsigned char* lds, const bf16_t* QB, const bf16_t* KB, const bf16_t* VT, bf16_t* OB, int b, int h, int qb, int wv) {
;     int tid_ = wv * 64 + hw_lane_id(); asm volatile("" : "+v"(tid_));
;     const int tid = tid_, lane = tid & 63, wid = __builtin_amdgcn_readfirstlane(tid >> 6), r = lane & 31, hh = lane >> 5;
;     const int q0 = qb * 512 + wid * 64;
;     const size_t rowbase = (size_t)b * SEQ;
;     bf16x8 qa[6], qbf[6];
;     { const bf16_t* qp = QB + (rowbase + q0 + r) * NQB + h * 96 + 8 * hh;
; #pragma unroll
;       for (int s = 0; s < 6; ++s) { qa[s] = *(const bf16x8*)(qp + 16 * s); qbf[s] = *(const bf16x8*)(qp + (size_t)32 * NQB + 16 * s); } }
;     f32x16 oa0, oa1, ob0, ob1;
; #pragma unroll
;     for (int i = 0; i < 16; ++i) { oa0[i] = 0.f; oa1[i] = 0.f; ob0[i] = 0.f; ob1[i] = 0.f; }
;     float ma = -INFINITY, mb = -INFINITY, la = 0.f, lb = 0.f;
;     const int ntiles = 8 * (qb + 1), nact = q0 / 64 + 1, tl = ntiles - 1;
;     const int kA_key = tid / 12, kA_part = tid % 12, kC_key = (512 + (tid & 255)) / 12, kC_part = (512 + (tid & 255)) % 12, v_d = tid >> 3, v_part = tid & 7;
;     const bf16_t* gKA = KB + (rowbase + kA_key) * NQB + h * 96 + kA_part * 8;
;     const bf16_t* gKC = KB + (rowbase + kC_key) * NQB + h * 96 + kC_part * 8;
;     const bf16_t* gV = VT + ((size_t)(b * 8 + h) * 64 + v_d) * SEQ + v_part * 8;
;     const int lKA = kA_key * MK_ROW + kA_part * 16, lKC = kC_key * MK_ROW + kC_part * 16, lV = MK_BYTES + v_d * MV_ROW + v_part * 16;
;     u32x4 ra = *(const u32x4*)gKA, rc = *(const u32x4*)gKC, rv = *(const u32x4*)gV;
;     __syncthreads();
;     *(LAS u32x4*)(lds + lKA) = ra; *(LAS u32x4*)(lds + lKC) = rc; *(LAS u32x4*)(lds + lV) = rv;
;     __syncthreads();
; #pragma unroll 1
;     for (int t = 0; t < ntiles; ++t) {
;         LAS unsigned char* cur = lds + (t & 1) * M2BUF;
;         { const int tn = (t + 1 < tl) ? t + 1 : tl;
;           ra = *(const u32x4*)(gKA + (size_t)tn * 64 * NQB); rc = *(const u32x4*)(gKC + (size_t)tn * 64 * NQB); rv = *(const u32x4*)(gV + tn * 64); }
.LBB0_660:
	v_mov_b32_e32 v20, v194
	s_mov_b32 s12, 0x2aaaaaab
	s_xor_b64 s[30:31], s[0:1], -1
	v_mul_hi_i32 v0, v20, s12
	v_lshrrev_b32_e32 v2, 31, v0
	v_ashrrev_i32_e32 v0, 1, v0
	v_add_u32_e32 v14, v0, v2
	v_mul_lo_u32 v0, v14, 12
	v_sub_u32_e32 v24, v20, v0
	v_mov_b32_e32 v0, 0xff
	s_movk_i32 s12, 0x200
	v_bitop3_b16 v0, v20, s12, v0 bitop3:0xec
	s_mov_b32 s12, 0xaaab
	v_mul_u32_u24_sdwa v2, v0, s12 dst_sel:DWORD dst_unused:UNUSED_PAD src0_sel:WORD_0 src1_sel:DWORD
	v_lshrrev_b32_e32 v25, 19, v2
	v_mul_lo_u16_e32 v2, 12, v25
	v_ashrrev_i32_e32 v15, 31, v14
	v_sub_u16_e32 v0, v0, v2
	v_lshl_add_u64 v[2:3], s[4:5], 0, v[14:15]
	v_mov_b64_e32 v[4:5], s[8:9]
	s_and_b64 s[0:1], s[0:1], exec
	v_mad_u64_u32 v[6:7], s[16:17], v2, s33, v[4:5]
	v_lshlrev_b32_e32 v2, 3, v24
	s_cselect_b32 s12, s69, s68
	v_readfirstlane_b32 s0, v20
	v_mad_i32_i24 v7, v3, s33, v7
	v_ashrrev_i32_e32 v3, 31, v2
	s_lshl_b32 s75, s12, 9
	s_and_b32 s70, s0, 0xffffffc0
	v_lshl_add_u64 v[200:201], v[2:3], 1, v[6:7]
	v_or_b32_e32 v2, s4, v25
	s_add_i32 s70, s70, s75
	v_ashrrev_i32_e32 v16, 3, v20
	v_mad_u64_u32 v[2:3], s[16:17], v2, s33, v[4:5]
	v_mov_b32_e32 v22, 0x600
	s_ashr_i32 s0, s70, 31
	v_mad_i32_i24 v3, s5, v22, v3
	v_lshlrev_b32_e32 v0, 4, v0
	v_ashrrev_i32_e32 v17, 31, v16
	v_and_b32_e32 v15, 31, v20
	s_add_u32 s1, s4, s70
	v_lshl_add_u64 v[202:203], v[2:3], 0, v[0:1]
	v_lshlrev_b64 v[2:3], 14, v[16:17]
	v_lshlrev_b32_e32 v12, 4, v20
	v_bfe_u32 v17, v20, 5, 1
	v_or_b32_e32 v198, s1, v15
	v_mov_b64_e32 v[20:21], s[6:7]
	s_addc_u32 s16, s5, s0
	v_mad_u64_u32 v[20:21], s[0:1], v198, s33, v[20:21]
	v_mad_i32_i24 v21, s16, v22, v21
	v_lshlrev_b32_e32 v206, 4, v17
	v_mov_b32_e32 v207, v1
	v_lshl_add_u64 v[10:11], s[10:11], 0, v[2:3]
	v_and_b32_e32 v18, 0x70, v12
	v_mov_b32_e32 v19, v1
	v_lshl_add_u64 v[20:21], v[20:21], 0, v[206:207]
	s_mov_b32 s0, 0xc000
	v_lshl_add_u64 v[204:205], v[10:11], 0, v[18:19]
	v_add_co_u32_e32 v22, vcc, s0, v20
	global_load_dwordx4 v[2:5], v[200:201], off
	global_load_dwordx4 v[6:9], v[202:203], off
	global_load_dwordx4 v[10:13], v[204:205], off
	global_load_dwordx4 v[144:147], v[20:21], off
	v_addc_co_u32_e32 v23, vcc, 0, v21, vcc
	global_load_dwordx4 v[148:151], v[20:21], off offset:32
	global_load_dwordx4 v[152:155], v[20:21], off offset:64
	global_load_dwordx4 v[156:159], v[22:23], off offset:32
	global_load_dwordx4 v[160:163], v[22:23], off offset:64
	global_load_dwordx4 v[164:167], v[20:21], off offset:96
	global_load_dwordx4 v[168:171], v[20:21], off offset:128
	global_load_dwordx4 v[172:175], v[22:23], off offset:96
	global_load_dwordx4 v[176:179], v[22:23], off offset:128
	global_load_dwordx4 v[180:183], v[22:23], off
	global_load_dwordx4 v[184:187], v[20:21], off offset:160
	global_load_dwordx4 v[188:191], v[22:23], off offset:160
	s_movk_i32 s0, 0xd0
	v_mul_lo_u32 v14, v14, s0
	v_mul_lo_u16_e32 v19, 0xd0, v25
	s_lshl_b32 s0, s12, 3
	v_lshl_add_u32 v197, v24, 4, v14
	v_add_u32_e32 v207, v0, v19
	s_or_b32 s73, s0, 7
	v_add_u32_e32 v0, 0, v197
	v_add_u32_e32 v14, 0, v207
	v_mad_u64_u32 v[208:209], s[0:1], v16, s19, v[18:19]
	s_or_b32 s74, s70, 32
	s_waitcnt vmcnt(63) expcnt(7) lgkmcnt(15)
	s_barrier
	v_mul_u32_u24_e32 v209, 0xd0, v15
	v_or_b32_e32 v211, s70, v15
	v_mul_u32_u24_e32 v213, 0x90, v15
	v_or_b32_e32 v214, s74, v15
	v_mov_b32_e32 v15, v1
	v_lshlrev_b32_e32 v196, 3, v17
	v_lshlrev_b32_e32 v212, 2, v17
	s_mov_b32 s71, 0
	s_ashr_i32 s72, s70, 6
	v_mov_b32_e32 v199, s16
	s_addk_i32 s75, 0x200
	v_mov_b32_e32 v223, 0xff800000
	s_waitcnt vmcnt(14)
	ds_write_b128 v0, v[2:5]
	s_waitcnt vmcnt(13)
	ds_write_b128 v14, v[6:9]
	v_add_u32_e32 v0, 0, v208
	v_mov_b32_e32 v14, v1
	s_waitcnt vmcnt(12)
	ds_write_b128 v0, v[10:13] offset:13312
	v_mov_b32_e32 v0, v1
	v_mov_b32_e32 v2, v1
	v_mov_b32_e32 v3, v1
	v_mov_b32_e32 v4, v1
	v_mov_b32_e32 v5, v1
	v_mov_b32_e32 v6, v1
	v_mov_b32_e32 v7, v1
	v_mov_b32_e32 v8, v1
	v_mov_b32_e32 v9, v1
	v_mov_b32_e32 v10, v1
	v_mov_b32_e32 v11, v1
	v_mov_b32_e32 v12, v1
	v_mov_b32_e32 v13, v1
	v_mov_b64_e32 v[30:31], v[14:15]
	v_mov_b64_e32 v[46:47], v[14:15]
	v_mov_b64_e32 v[62:63], v[14:15]
	v_mov_b64_e32 v[78:79], v[14:15]
	v_mov_b32_e32 v222, 0
	s_mov_b32 s0, 0
	v_mov_b32_e32 v225, 0
	v_mov_b32_e32 v224, 0xff800000
	v_mov_b64_e32 v[28:29], v[12:13]
	v_mov_b64_e32 v[26:27], v[10:11]
	v_mov_b64_e32 v[24:25], v[8:9]
	v_mov_b64_e32 v[22:23], v[6:7]
	v_mov_b64_e32 v[20:21], v[4:5]
	v_mov_b64_e32 v[18:19], v[2:3]
	v_mov_b64_e32 v[16:17], v[0:1]
	v_mov_b64_e32 v[44:45], v[12:13]
	v_mov_b64_e32 v[42:43], v[10:11]
	v_mov_b64_e32 v[40:41], v[8:9]
	v_mov_b64_e32 v[38:39], v[6:7]
	v_mov_b64_e32 v[36:37], v[4:5]
	v_mov_b64_e32 v[34:35], v[2:3]
	v_mov_b64_e32 v[32:33], v[0:1]
	v_mov_b64_e32 v[60:61], v[12:13]
	v_mov_b64_e32 v[58:59], v[10:11]
	v_mov_b64_e32 v[56:57], v[8:9]
	v_mov_b64_e32 v[54:55], v[6:7]
	v_mov_b64_e32 v[52:53], v[4:5]
	v_mov_b64_e32 v[50:51], v[2:3]
	v_mov_b64_e32 v[48:49], v[0:1]
	v_mov_b64_e32 v[76:77], v[12:13]
	v_mov_b64_e32 v[74:75], v[10:11]
	v_mov_b64_e32 v[72:73], v[8:9]
	v_mov_b64_e32 v[70:71], v[6:7]
	v_mov_b64_e32 v[68:69], v[4:5]
	v_mov_b64_e32 v[66:67], v[2:3]
	v_mov_b64_e32 v[64:65], v[0:1]
	s_mov_b32 s99, 0
	s_min_u32 s98, s73, 1
	s_mul_i32 s98, s98, 0x18000
	v_lshl_add_u64 v[2:3], v[200:201], 0, s[98:99]
	v_lshl_add_u64 v[4:5], v[202:203], 0, s[98:99]
	global_load_dwordx4 v[6:9], v[2:3], off
	s_nop 0
	global_load_dwordx4 v[2:5], v[4:5], off
	s_waitcnt lgkmcnt(0)
	s_barrier
	s_bitcmp1_b32 s72, 2
	s_cbranch_scc0 .Lmla_nostag
	s_barrier
; #define LAS __attribute__((address_space(3)))
; #define MFMA32(a, b, c) __builtin_amdgcn_mfma_f32_32x32x16_bf16((a), (b), (c), 0, 0, 0)
; __device__ __forceinline__ int crow(int i, int hh) { return (i & 3) + 8 * (i >> 2) + 4 * hh; }
; __device__ __forceinline__ void mla_softmax(f32x16& s0, f32x16& s1, f32x16& o0, f32x16& o1, float& m, float& l, int k0, int qrow0, int r, int hh) {
;     if (k0 + 63 > qrow0) {
;         const int qpos = qrow0 + r;
; #pragma unroll
;         for (int i = 0; i < 16; ++i) { const int kp = k0 + crow(i, hh); if (kp > qpos) s0[i] = -INFINITY; if (kp + 32 > qpos) s1[i] = -INFINITY; }
;     }
; __device__ __forceinline__ void mla_unit2(LAS unsigned char* lds, const bf16_t* QB, const bf16_t* KB, const bf16_t* VT, bf16_t* OB, int b, int h, int qb, int wv) {
;     ...
;     for (int t = 0; t < ntiles; ++t) {
;         LAS unsigned char* cur = lds + (t & 1) * M2BUF;
;         { const int tn = (t + 1 < tl) ? t + 1 : tl;
;           ra = *(const u32x4*)(gKA + (size_t)tn * 64 * NQB); rc = *(const u32x4*)(gKC + (size_t)tn * 64 * NQB); rv = *(const u32x4*)(gV + tn * 64); }
;         if (t < nact) {
;             const int k0 = t * 64;
;             f32x16 sa0, sa1, sb0, sb1;
;             { const LAS unsigned char* kp = cur + r * MK_ROW + hh * 16;
; #pragma unroll
;               for (int i = 0; i < 16; ++i) { sa0[i] = 0.f; sa1[i] = 0.f; sb0[i] = 0.f; sb1[i] = 0.f; }
; #pragma unroll
;               for (int hf = 0; hf < 2; ++hf) {
;                   bf16x8 ka[3], kc[3];
; #pragma unroll
;                   for (int s = 0; s < 3; ++s) { ka[s] = *(const LAS bf16x8*)(kp + (3 * hf + s) * 32); kc[s] = *(const LAS bf16x8*)(kp + 32 * MK_ROW + (3 * hf + s) * 32); }
;                   __builtin_amdgcn_sched_barrier(0);
; #pragma unroll
;                   for (int s = 0; s < 3; ++s) { sa0 = MFMA32(ka[s], qa[3 * hf + s], sa0); sa1 = MFMA32(kc[s], qa[3 * hf + s], sa1); sb0 = MFMA32(ka[s], qbf[3 * hf + s], sb0); sb1 = MFMA32(kc[s], qbf[3 * hf + s], sb1); }
;                   __builtin_amdgcn_sched_barrier(0);
;               } }
.Lmla_nostag:
.LBB0_661:
	s_add_i32 s76, s0, 1
	s_mov_b32 s100, s0
	s_min_u32 s1, s76, s73
	s_lshl_b32 s98, s1, 7
	v_lshl_add_u64 v[10:11], v[204:205], 0, s[98:99]
	s_cmp_gt_i32 s0, s72
	global_load_dwordx4 v[10:13], v[10:11], off
	s_cbranch_scc1 .Lmla_kstage
	s_bitcmp1_b32 s0, 0
	s_cselect_b32 s0, 0x5800, 0
	s_add_i32 s12, s0, 0
	v_add3_u32 v0, s12, v209, v206
	ds_read_b128 v[80:83], v0
	ds_read_b128 v[226:229], v0 offset:32
	ds_read_b128 v[84:87], v0 offset:6656
	ds_read_b128 v[230:233], v0 offset:64
	ds_read_b128 v[234:237], v0 offset:6688
	ds_read_b128 v[238:241], v0 offset:6720
	s_waitcnt vmcnt(14) lgkmcnt(5)
	v_mfma_f32_32x32x16_bf16 v[128:143], v[80:83], v[144:147], 0
	s_waitcnt lgkmcnt(3)
	v_mfma_f32_32x32x16_bf16 v[112:127], v[84:87], v[144:147], 0
	s_waitcnt vmcnt(5)
	v_mfma_f32_32x32x16_bf16 v[96:111], v[80:83], v[180:183], 0
	v_mfma_f32_32x32x16_bf16 v[80:95], v[84:87], v[180:183], 0
	v_mfma_f32_32x32x16_bf16 v[128:143], v[226:229], v[148:151], v[128:143]
	s_waitcnt lgkmcnt(1)
	v_mfma_f32_32x32x16_bf16 v[112:127], v[234:237], v[148:151], v[112:127]
	v_mfma_f32_32x32x16_bf16 v[96:111], v[226:229], v[156:159], v[96:111]
	v_mfma_f32_32x32x16_bf16 v[80:95], v[234:237], v[156:159], v[80:95]
	v_mfma_f32_32x32x16_bf16 v[128:143], v[230:233], v[152:155], v[128:143]
	s_waitcnt lgkmcnt(0)
	v_mfma_f32_32x32x16_bf16 v[112:127], v[238:241], v[152:155], v[112:127]
	v_mfma_f32_32x32x16_bf16 v[96:111], v[230:233], v[160:163], v[96:111]
	v_mfma_f32_32x32x16_bf16 v[80:95], v[238:241], v[160:163], v[80:95]
	ds_read_b128 v[226:229], v0 offset:96
	ds_read_b128 v[230:233], v0 offset:128
	ds_read_b128 v[234:237], v0 offset:6752
	ds_read_b128 v[238:241], v0 offset:160
	ds_read_b128 v[242:245], v0 offset:6784
	ds_read_b128 v[246:249], v0 offset:6816
	s_waitcnt lgkmcnt(5)
	v_mfma_f32_32x32x16_bf16 v[128:143], v[226:229], v[164:167], v[128:143]
	s_waitcnt lgkmcnt(3)
	v_mfma_f32_32x32x16_bf16 v[112:127], v[234:237], v[164:167], v[112:127]
	v_mfma_f32_32x32x16_bf16 v[96:111], v[226:229], v[172:175], v[96:111]
	v_mfma_f32_32x32x16_bf16 v[80:95], v[234:237], v[172:175], v[80:95]
	v_mfma_f32_32x32x16_bf16 v[128:143], v[230:233], v[168:171], v[128:143]
	s_waitcnt lgkmcnt(1)
	v_mfma_f32_32x32x16_bf16 v[112:127], v[242:245], v[168:171], v[112:127]
	v_mfma_f32_32x32x16_bf16 v[96:111], v[230:233], v[176:179], v[96:111]
	v_mfma_f32_32x32x16_bf16 v[80:95], v[242:245], v[176:179], v[80:95]
	s_waitcnt vmcnt(4)
	v_mfma_f32_32x32x16_bf16 v[128:143], v[238:241], v[184:187], v[128:143]
	s_waitcnt lgkmcnt(0)
	v_mfma_f32_32x32x16_bf16 v[112:127], v[246:249], v[184:187], v[112:127]
	s_waitcnt vmcnt(3)
	v_mfma_f32_32x32x16_bf16 v[96:111], v[238:241], v[188:191], v[96:111]
	v_mfma_f32_32x32x16_bf16 v[80:95], v[246:249], v[188:191], v[80:95]
	s_add_i32 s25, s71, 63
	s_cmp_le_i32 s25, s70
	s_nop 7
	s_cbranch_scc1 .LBB0_666
	v_add_u32_e32 v249, s71, v212
	v_add_u32_e32 v192, 32, v249
	v_add_u32_e32 v219, 33, v249
	v_add_u32_e32 v250, 2, v249
	v_add_u32_e32 v251, 34, v249
	v_add_u32_e32 v247, 3, v249
	v_add_u32_e32 v248, 35, v249
	v_add_u32_e32 v245, 8, v249
	v_add_u32_e32 v246, 40, v249
	v_add_u32_e32 v243, 9, v249
	v_add_u32_e32 v244, 41, v249
	v_add_u32_e32 v241, 10, v249
	v_add_u32_e32 v242, 42, v249
	v_add_u32_e32 v239, 11, v249
	v_add_u32_e32 v240, 43, v249
	v_add_u32_e32 v237, 16, v249
	v_add_u32_e32 v238, 48, v249
	v_add_u32_e32 v235, 17, v249
	v_add_u32_e32 v236, 49, v249
	v_add_u32_e32 v233, 18, v249
	v_add_u32_e32 v234, 50, v249
	v_add_u32_e32 v231, 19, v249
	v_add_u32_e32 v232, 51, v249
	v_add_u32_e32 v229, 24, v249
	v_add_u32_e32 v230, 56, v249
	v_add_u32_e32 v227, 25, v249
	v_add_u32_e32 v228, 57, v249
	v_add_u32_e32 v210, 26, v249
	v_add_u32_e32 v226, 58, v249
	v_add_u32_e32 v0, 27, v249
	v_add_u32_e32 v15, 59, v249
	v_cmp_le_i32_e64 s[0:1], v192, v211
	v_cmp_le_i32_e64 s[36:37], v219, v211
	v_cmp_le_i32_e64 s[38:39], v251, v211
	v_cmp_le_i32_e64 s[40:41], v248, v211
	v_cmp_le_i32_e64 s[42:43], v246, v211
	v_cmp_le_i32_e64 s[44:45], v244, v211
	v_cmp_le_i32_e64 s[46:47], v242, v211
	v_cmp_le_i32_e64 s[48:49], v240, v211
	v_cmp_le_i32_e64 s[50:51], v238, v211
	v_cmp_le_i32_e64 s[52:53], v236, v211
	v_cmp_le_i32_e64 s[54:55], v234, v211
	v_cmp_le_i32_e64 s[56:57], v232, v211
	v_cmp_le_i32_e64 s[58:59], v230, v211
	v_cmp_le_i32_e64 s[60:61], v228, v211
	v_cmp_le_i32_e64 s[62:63], v226, v211
	v_cmp_le_i32_e32 vcc, v249, v211
	v_cndmask_b32_e64 v112, v221, v112, s[0:1]
	v_cmp_lt_i32_e64 s[0:1], v249, v211
	v_cndmask_b32_e64 v113, v221, v113, s[36:37]
	v_cmp_le_i32_e64 s[36:37], v250, v211
	v_cndmask_b32_e64 v114, v221, v114, s[38:39]
	v_cmp_le_i32_e64 s[38:39], v247, v211
	v_cndmask_b32_e64 v115, v221, v115, s[40:41]
	v_cmp_le_i32_e64 s[40:41], v245, v211
	v_cndmask_b32_e64 v116, v221, v116, s[42:43]
	v_cmp_le_i32_e64 s[42:43], v243, v211
	v_cndmask_b32_e64 v117, v221, v117, s[44:45]
	v_cmp_le_i32_e64 s[44:45], v241, v211
	v_cndmask_b32_e64 v118, v221, v118, s[46:47]
	v_cmp_le_i32_e64 s[46:47], v239, v211
	v_cndmask_b32_e64 v119, v221, v119, s[48:49]
	v_cmp_le_i32_e64 s[48:49], v237, v211
	v_cndmask_b32_e64 v120, v221, v120, s[50:51]
	v_cmp_le_i32_e64 s[50:51], v235, v211
	v_cndmask_b32_e64 v121, v221, v121, s[52:53]
	v_cmp_le_i32_e64 s[52:53], v233, v211
	v_cndmask_b32_e64 v122, v221, v122, s[54:55]
	v_cmp_le_i32_e64 s[54:55], v231, v211
	v_cndmask_b32_e64 v123, v221, v123, s[56:57]
	v_cmp_le_i32_e64 s[56:57], v229, v211
	v_cndmask_b32_e64 v124, v221, v124, s[58:59]
	v_cmp_le_i32_e64 s[58:59], v227, v211
	v_cndmask_b32_e64 v125, v221, v125, s[60:61]
	v_cmp_le_i32_e64 s[60:61], v210, v211
	v_cndmask_b32_e64 v126, v221, v126, s[62:63]
	v_cmp_le_i32_e64 s[62:63], v0, v211
	v_cmp_gt_i32_e64 s[64:65], v15, v211
	s_and_saveexec_b64 s[16:17], s[64:65]
	v_mov_b32_e32 v127, s2
	s_or_b64 exec, exec, s[16:17]
	v_cndmask_b32_e64 v129, v221, v129, s[0:1]
	v_cndmask_b32_e32 v128, v221, v128, vcc
	v_cndmask_b32_e64 v130, v221, v130, s[36:37]
	v_cndmask_b32_e64 v131, v221, v131, s[38:39]
	v_cndmask_b32_e64 v132, v221, v132, s[40:41]
	v_cndmask_b32_e64 v133, v221, v133, s[42:43]
	v_cndmask_b32_e64 v134, v221, v134, s[44:45]
	v_cndmask_b32_e64 v135, v221, v135, s[46:47]
	v_cndmask_b32_e64 v136, v221, v136, s[48:49]
	v_cndmask_b32_e64 v137, v221, v137, s[50:51]
	v_cndmask_b32_e64 v138, v221, v138, s[52:53]
	v_cndmask_b32_e64 v139, v221, v139, s[54:55]
	v_cndmask_b32_e64 v140, v221, v140, s[56:57]
	v_cndmask_b32_e64 v141, v221, v141, s[58:59]
	v_cndmask_b32_e64 v142, v221, v142, s[60:61]
	v_cndmask_b32_e64 v143, v221, v143, s[62:63]

; #define LAS __attribute__((address_space(3)))
; #define MFMA32(a, b, c) __builtin_amdgcn_mfma_f32_32x32x16_bf16((a), (b), (c), 0, 0, 0)
; __device__ __forceinline__ void mla_softmax(f32x16& s0, f32x16& s1, f32x16& o0, f32x16& o1, float& m, float& l, int k0, int qrow0, int r, int hh) {
;     ...
;     float ps = 0.f;
; #pragma unroll
;     for (int i = 0; i < 16; ++i) { s0[i] = __builtin_amdgcn_exp2f(s0[i] - m); s1[i] = __builtin_amdgcn_exp2f(s1[i] - m); ps += s0[i] + s1[i]; }
;     l = l * alpha + ps;
; __device__ __forceinline__ void mla_unit2(LAS unsigned char* lds, const bf16_t* QB, const bf16_t* KB, const bf16_t* VT, bf16_t* OB, int b, int h, int qb, int wv) {
;     ...
;             mla_softmax(sa0, sa1, oa0, oa1, ma, la, k0, q0, r, hh);
;             const LAS unsigned char* vb = cur + MK_BYTES + r * MV_ROW + hh * 16;
;             mla_softmax(sb0, sb1, ob0, ob1, mb, lb, k0, q0 + 32, r, hh);
;             bf16x8 v0 = *(const LAS bf16x8*)vb, v1 = *(const LAS bf16x8*)(vb + 32 * MV_ROW);
; #pragma unroll
;             for (int ks = 0; ks < 4; ++ks) {
;                 bf16x8 n0 = v0, n1 = v1;
;                 if (ks < 3) { n0 = *(const LAS bf16x8*)(vb + (ks + 1) * 32); n1 = *(const LAS bf16x8*)(vb + 32 * MV_ROW + (ks + 1) * 32); }
;                 const bf16x8 pa = (ks < 2) ? pack8(sa0, 8 * (ks & 1)) : pack8(sa1, 8 * (ks & 1));
;                 const bf16x8 pb = (ks < 2) ? pack8(sb0, 8 * (ks & 1)) : pack8(sb1, 8 * (ks & 1));
;                 oa0 = MFMA32(v0, pa, oa0); oa1 = MFMA32(v1, pa, oa1); ob0 = MFMA32(v0, pb, ob0); ob1 = MFMA32(v1, pb, ob1);
;                 v0 = n0; v1 = n1;
;             }
.LBB0_675:
.Lmla_kstage:
	s_bitcmp1_b32 s76, 0
	s_cselect_b32 s1, 0x5800, 0
	v_add_u32_e32 v0, s1, v197
	v_add_u32_e32 v15, s1, v207
	s_waitcnt vmcnt(1)
	ds_write_b128 v0, v[6:9]
	ds_write_b128 v15, v[2:5]
	s_add_i32 s1, s76, 1
	s_min_u32 s1, s1, s73
	s_mul_i32 s98, s1, 0x18000
	s_waitcnt lgkmcnt(0)
	s_barrier
	v_lshl_add_u64 v[2:3], v[200:201], 0, s[98:99]
	v_lshl_add_u64 v[4:5], v[202:203], 0, s[98:99]
	s_cmp_gt_i32 s100, s72
	global_load_dwordx4 v[6:9], v[2:3], off
	s_nop 0
	global_load_dwordx4 v[2:5], v[4:5], off
	s_cbranch_scc1 .LBB0_676
	v_sub_f32_e32 v0, v128, v224
	v_exp_f32_e32 v15, v0
	v_sub_f32_e32 v0, v112, v224
	v_exp_f32_e32 v192, v0
	v_sub_f32_e32 v0, v129, v224
	v_exp_f32_e32 v128, v0
	v_sub_f32_e32 v0, v113, v224
	v_sub_f32_e32 v113, v131, v224
	v_exp_f32_e32 v193, v0
	v_sub_f32_e32 v0, v130, v224
	v_exp_f32_e32 v130, v113
	v_sub_f32_e32 v113, v115, v224
	v_exp_f32_e32 v195, v113
	v_sub_f32_e32 v113, v132, v224
	v_exp_f32_e32 v131, v113
	v_sub_f32_e32 v113, v116, v224
	v_exp_f32_e32 v215, v113
	v_sub_f32_e32 v113, v133, v224
	v_exp_f32_e32 v132, v113
	v_sub_f32_e32 v113, v117, v224
	v_exp_f32_e32 v133, v113
	v_sub_f32_e32 v113, v134, v224
	v_exp_f32_e32 v134, v113
	v_sub_f32_e32 v113, v118, v224
	v_exp_f32_e32 v218, v113
	v_sub_f32_e32 v113, v135, v224
	v_exp_f32_e32 v135, v113
	v_sub_f32_e32 v113, v119, v224
	v_exp_f32_e32 v219, v113
	v_sub_f32_e32 v113, v136, v224
	v_exp_f32_e32 v129, v0
	v_sub_f32_e32 v0, v114, v224
	v_exp_f32_e32 v136, v113
	v_sub_f32_e32 v113, v120, v224
	v_exp_f32_e32 v194, v0
	v_exp_f32_e32 v226, v113
	v_sub_f32_e32 v113, v137, v224
	v_exp_f32_e32 v137, v113
	v_sub_f32_e32 v113, v121, v224
	v_add_f32_e32 v112, v192, v15
	v_exp_f32_e32 v227, v113
	v_sub_f32_e32 v113, v138, v224
	v_add_f32_e32 v0, 0, v112
	v_add_f32_e32 v112, v193, v128
	v_exp_f32_e32 v138, v113
	v_sub_f32_e32 v113, v122, v224
	v_add_f32_e32 v0, v112, v0
	v_add_f32_e32 v112, v194, v129
	v_exp_f32_e32 v228, v113
	v_sub_f32_e32 v113, v139, v224
	v_add_f32_e32 v0, v112, v0
	v_add_f32_e32 v112, v195, v130
	v_exp_f32_e32 v139, v113
	v_sub_f32_e32 v113, v123, v224
	v_add_f32_e32 v0, v112, v0
	v_add_f32_e32 v112, v215, v131
	v_exp_f32_e32 v229, v113
	v_sub_f32_e32 v113, v140, v224
	v_add_f32_e32 v0, v112, v0
	v_add_f32_e32 v112, v133, v132
	v_exp_f32_e32 v140, v113
	v_sub_f32_e32 v113, v124, v224
	v_add_f32_e32 v0, v112, v0
	v_add_f32_e32 v112, v218, v134
	v_exp_f32_e32 v230, v113
	v_sub_f32_e32 v113, v141, v224
	v_add_f32_e32 v0, v112, v0
	v_add_f32_e32 v112, v219, v135
	v_exp_f32_e32 v141, v113
	v_sub_f32_e32 v113, v125, v224
	v_add_f32_e32 v0, v112, v0
	v_add_f32_e32 v112, v226, v136
	v_exp_f32_e32 v125, v113
	v_sub_f32_e32 v113, v142, v224
	v_add_f32_e32 v0, v112, v0
	v_add_f32_e32 v112, v227, v137
	v_exp_f32_e32 v142, v113
	v_sub_f32_e32 v113, v126, v224
	v_add_f32_e32 v0, v112, v0
	v_add_f32_e32 v112, v228, v138
	v_exp_f32_e32 v231, v113
	v_add_f32_e32 v0, v112, v0
	v_add_f32_e32 v112, v229, v139
	v_add_f32_e32 v0, v112, v0
	v_add_f32_e32 v112, v230, v140
	v_add_f32_e32 v0, v112, v0
	v_add_f32_e32 v112, v125, v141
	v_add_f32_e32 v0, v112, v0
	v_add_f32_e32 v112, v231, v142
	v_add3_u32 v234, s12, v213, v206
	v_add_f32_e32 v232, v112, v0
	ds_read_b128 v[112:115], v234 offset:13312
	v_sub_f32_e32 v0, v96, v223
	v_sub_f32_e32 v96, v98, v223
	v_exp_f32_e32 v233, v0
	v_sub_f32_e32 v0, v97, v223
	v_exp_f32_e32 v235, v96
	v_sub_f32_e32 v124, v99, v223
	ds_read_b128 v[96:99], v234 offset:17920
	ds_read_b128 v[116:119], v234 offset:13344
	v_cvt_pk_bf16_f32 v120, v15, v128
	v_sub_f32_e32 v15, v100, v223
	v_sub_f32_e32 v100, v101, v223
	v_cvt_pk_bf16_f32 v121, v129, v130
	v_cvt_pk_bf16_f32 v122, v131, v132
	v_cvt_pk_bf16_f32 v123, v134, v135
	v_exp_f32_e32 v126, v100
	v_sub_f32_e32 v100, v102, v223
	s_waitcnt lgkmcnt(2)
	v_mfma_f32_32x32x16_bf16 v[64:79], v[112:115], v[120:123], v[64:79]
	v_exp_f32_e32 v0, v0
	v_exp_f32_e32 v124, v124
	v_exp_f32_e32 v15, v15
	ds_read_b128 v[128:131], v234 offset:17952
	v_sub_f32_e32 v104, v104, v223
	v_cvt_pk_bf16_f32 v101, v235, v124
	v_cvt_pk_bf16_f32 v102, v15, v126
	s_waitcnt lgkmcnt(2)
	v_mfma_f32_32x32x16_bf16 v[48:63], v[96:99], v[120:123], v[48:63]
	v_exp_f32_e32 v121, v100
	v_sub_f32_e32 v100, v103, v223
	v_exp_f32_e32 v120, v100
	v_cvt_pk_bf16_f32 v100, v233, v0
	v_exp_f32_e32 v123, v104
	v_sub_f32_e32 v104, v105, v223
	v_cvt_pk_bf16_f32 v103, v121, v120
	v_sub_f32_e32 v80, v80, v223
	v_sub_f32_e32 v84, v84, v223
	v_mfma_f32_32x32x16_bf16 v[32:47], v[112:115], v[100:103], v[32:47]
	v_sub_f32_e32 v112, v143, v224
	v_exp_f32_e32 v113, v112
	v_sub_f32_e32 v112, v127, v224
	v_exp_f32_e32 v115, v112
	v_exp_f32_e32 v112, v104
	v_cvt_pk_bf16_f32 v104, v192, v193
	v_cvt_pk_bf16_f32 v105, v194, v195
	v_mfma_f32_32x32x16_bf16 v[16:31], v[96:99], v[100:103], v[16:31]
	v_sub_f32_e32 v100, v107, v223
	v_exp_f32_e32 v114, v100
	v_sub_f32_e32 v100, v108, v223
	v_sub_f32_e32 v96, v106, v223
	v_exp_f32_e32 v134, v100
	v_sub_f32_e32 v100, v109, v223
	v_exp_f32_e32 v127, v96
	v_cvt_pk_bf16_f32 v96, v136, v137
	v_cvt_pk_bf16_f32 v97, v138, v139
	v_cvt_pk_bf16_f32 v98, v140, v141
	v_cvt_pk_bf16_f32 v99, v142, v113
	v_exp_f32_e32 v122, v100
	v_sub_f32_e32 v100, v110, v223
	s_waitcnt lgkmcnt(1)
; #define LAS __attribute__((address_space(3)))
; #define MFMA32(a, b, c) __builtin_amdgcn_mfma_f32_32x32x16_bf16((a), (b), (c), 0, 0, 0)
; __device__ __forceinline__ void mla_unit2(LAS unsigned char* lds, const bf16_t* QB, const bf16_t* KB, const bf16_t* VT, bf16_t* OB, int b, int h, int qb, int wv) {
;     ...
;             mla_softmax(sa0, sa1, oa0, oa1, ma, la, k0, q0, r, hh);
;             const LAS unsigned char* vb = cur + MK_BYTES + r * MV_ROW + hh * 16;
;             mla_softmax(sb0, sb1, ob0, ob1, mb, lb, k0, q0 + 32, r, hh);
;             bf16x8 v0 = *(const LAS bf16x8*)vb, v1 = *(const LAS bf16x8*)(vb + 32 * MV_ROW);
; #pragma unroll
;             for (int ks = 0; ks < 4; ++ks) {
;                 bf16x8 n0 = v0, n1 = v1;
;                 if (ks < 3) { n0 = *(const LAS bf16x8*)(vb + (ks + 1) * 32); n1 = *(const LAS bf16x8*)(vb + 32 * MV_ROW + (ks + 1) * 32); }
;                 const bf16x8 pa = (ks < 2) ? pack8(sa0, 8 * (ks & 1)) : pack8(sa1, 8 * (ks & 1));
;                 const bf16x8 pb = (ks < 2) ? pack8(sb0, 8 * (ks & 1)) : pack8(sb1, 8 * (ks & 1));
;                 oa0 = MFMA32(v0, pa, oa0); oa1 = MFMA32(v1, pa, oa1); ob0 = MFMA32(v0, pb, ob0); ob1 = MFMA32(v1, pb, ob1);
;                 v0 = n0; v1 = n1;
;             }
;         }
;         { LAS unsigned char* nxt = lds + ((t + 1) & 1) * M2BUF;
;           *(LAS u32x4*)(nxt + lKA) = ra; *(LAS u32x4*)(nxt + lKC) = rc; *(LAS u32x4*)(nxt + lV) = rv; }
;         __syncthreads();
;     }
	v_mfma_f32_32x32x16_bf16 v[64:79], v[116:119], v[96:99], v[64:79]
	v_exp_f32_e32 v135, v100
	ds_read_b128 v[100:103], v234 offset:13376
	v_sub_f32_e32 v108, v83, v223
	v_cvt_pk_bf16_f32 v106, v215, v133
	v_cvt_pk_bf16_f32 v107, v218, v219
	s_waitcnt lgkmcnt(1)
	v_mfma_f32_32x32x16_bf16 v[48:63], v[128:131], v[96:99], v[48:63]
	v_sub_f32_e32 v96, v111, v223
	v_exp_f32_e32 v132, v96
	v_cvt_pk_bf16_f32 v96, v123, v112
	v_cvt_pk_bf16_f32 v97, v127, v114
	v_cvt_pk_bf16_f32 v98, v134, v122
	v_cvt_pk_bf16_f32 v99, v135, v132
	s_waitcnt lgkmcnt(0)
	v_mfma_f32_32x32x16_bf16 v[64:79], v[100:103], v[104:107], v[64:79]
	v_mfma_f32_32x32x16_bf16 v[32:47], v[116:119], v[96:99], v[32:47]
	v_exp_f32_e32 v117, v80
	v_sub_f32_e32 v80, v81, v223
	v_exp_f32_e32 v116, v80
	v_sub_f32_e32 v80, v82, v223
	v_exp_f32_e32 v119, v80
	v_exp_f32_e32 v118, v108
	v_mfma_f32_32x32x16_bf16 v[16:31], v[128:131], v[96:99], v[16:31]
	ds_read_b128 v[80:83], v234 offset:17984
	ds_read_b128 v[96:99], v234 offset:13408
	v_exp_f32_e32 v129, v84
	v_sub_f32_e32 v84, v85, v223
	v_exp_f32_e32 v128, v84
	v_sub_f32_e32 v84, v86, v223
	ds_read_b128 v[108:111], v234 offset:18016
	v_cvt_pk_bf16_f32 v85, v119, v118
	s_waitcnt lgkmcnt(2)
	v_mfma_f32_32x32x16_bf16 v[48:63], v[80:83], v[104:107], v[48:63]
	v_exp_f32_e32 v105, v84
	v_sub_f32_e32 v84, v87, v223
	v_exp_f32_e32 v104, v84
	v_cvt_pk_bf16_f32 v84, v117, v116
	v_cvt_pk_bf16_f32 v86, v129, v128
	v_add_f32_e32 v117, v117, v233
	v_cvt_pk_bf16_f32 v87, v105, v104
	v_add_f32_e32 v119, v119, v235
	v_add_f32_e32 v129, v129, v15
	v_mfma_f32_32x32x16_bf16 v[32:47], v[100:103], v[84:87], v[32:47]
	v_add_f32_e32 v100, v115, v113
	v_add_f32_e32 v100, v100, v232
	v_fmac_f32_e32 v100, v225, v14
	v_sub_f32_e32 v14, v88, v223
	v_exp_f32_e32 v101, v14
	v_sub_f32_e32 v14, v89, v223
	v_sub_f32_e32 v88, v94, v223
	v_mfma_f32_32x32x16_bf16 v[16:31], v[80:83], v[84:87], v[16:31]
	v_sub_f32_e32 v80, v90, v223
	v_exp_f32_e32 v85, v80
	v_cvt_pk_bf16_f32 v80, v226, v227
	v_cvt_pk_bf16_f32 v81, v228, v229
	v_cvt_pk_bf16_f32 v82, v230, v125
	v_cvt_pk_bf16_f32 v83, v231, v115
	v_sub_f32_e32 v86, v92, v223
	v_sub_f32_e32 v84, v91, v223
	s_waitcnt lgkmcnt(1)
	v_mfma_f32_32x32x16_bf16 v[64:79], v[96:99], v[80:83], v[64:79]
	v_exp_f32_e32 v87, v86
	v_sub_f32_e32 v86, v93, v223
	v_exp_f32_e32 v14, v14
	v_exp_f32_e32 v84, v84
	v_exp_f32_e32 v86, v86
	v_exp_f32_e32 v89, v88
	v_add_f32_e32 v105, v105, v121
	s_waitcnt lgkmcnt(0)
	v_mfma_f32_32x32x16_bf16 v[48:63], v[108:111], v[80:83], v[48:63]
	v_sub_f32_e32 v80, v95, v223
	v_exp_f32_e32 v88, v80
	v_cvt_pk_bf16_f32 v80, v101, v14
	v_cvt_pk_bf16_f32 v81, v85, v84
	v_cvt_pk_bf16_f32 v82, v87, v86
	v_cvt_pk_bf16_f32 v83, v89, v88
	v_add_f32_e32 v85, v85, v127
	v_add_f32_e32 v15, v101, v123
	v_mfma_f32_32x32x16_bf16 v[32:47], v[96:99], v[80:83], v[32:47]
	v_add_f32_e32 v87, v87, v134
	v_add_f32_e32 v89, v89, v135
	v_mov_b32_e32 v225, v100
	v_mfma_f32_32x32x16_bf16 v[16:31], v[108:111], v[80:83], v[16:31]
	v_add_f32_e32 v80, v116, v0
	v_add_f32_e32 v80, v80, v117
	v_add_f32_e32 v81, v118, v124
	v_add_f32_e32 v80, v80, v119
	v_add_f32_e32 v80, v80, v81
	v_add_f32_e32 v81, v128, v126
	v_add_f32_e32 v80, v80, v129
	v_add_f32_e32 v80, v80, v81
	v_add_f32_e32 v81, v104, v120
	v_add_f32_e32 v80, v80, v105
	v_add_f32_e32 v80, v80, v81
	v_add_f32_e32 v81, v14, v112
	v_add_f32_e32 v80, v80, v15
	v_add_f32_e32 v80, v80, v81
	v_add_f32_e32 v81, v84, v114
	v_add_f32_e32 v80, v80, v85
	v_add_f32_e32 v80, v80, v81
	v_add_f32_e32 v81, v86, v122
	v_add_f32_e32 v80, v80, v87
	v_add_f32_e32 v80, v80, v81
	v_add_f32_e32 v81, v88, v132
	v_add_f32_e32 v80, v80, v89
	v_add_f32_e32 v0, v80, v81
	v_fmac_f32_e32 v0, v222, v210
	v_mov_b32_e32 v222, v0
.LBB0_676:
	s_bitcmp1_b32 s76, 0
	s_cselect_b32 s0, 0x5800, 0
	v_add_u32_e32 v0, s0, v208
	s_add_i32 s71, s71, 64
	s_cmp_lg_u32 s75, s71
	s_waitcnt vmcnt(2)
	ds_write_b128 v0, v[10:13] offset:13312
	s_waitcnt lgkmcnt(0)
	s_barrier
	s_cbranch_scc0 .Lmla_exit
	s_mov_b32 s0, s76
	s_branch .LBB0_661
.Lmla_exit:
	s_waitcnt vmcnt(0)
	s_bitcmp1_b32 s72, 2
	s_cbranch_scc1 .LBB0_659
	s_barrier
	s_branch .LBB0_659

; __global__ void __launch_bounds__(512) fwd_megakernel(Params p) {
	.amdhsa_kernel _Z14fwd_megakernel6Params
		.amdhsa_group_segment_fixed_size 0
		.amdhsa_private_segment_fixed_size 0
		.amdhsa_kernarg_size 408
		.amdhsa_user_sgpr_count 2
		.amdhsa_user_sgpr_dispatch_ptr 0
		.amdhsa_user_sgpr_queue_ptr 0
		.amdhsa_user_sgpr_kernarg_segment_ptr 1
		.amdhsa_user_sgpr_dispatch_id 0
		.amdhsa_user_sgpr_kernarg_preload_length 0
		.amdhsa_user_sgpr_kernarg_preload_offset 0
		.amdhsa_user_sgpr_private_segment_size 0
		.amdhsa_uses_dynamic_stack 0
		.amdhsa_enable_private_segment 0
		.amdhsa_system_sgpr_workgroup_id_x 1
		.amdhsa_system_sgpr_workgroup_id_y 0
		.amdhsa_system_sgpr_workgroup_id_z 0
		.amdhsa_system_sgpr_workgroup_info 0
		.amdhsa_system_vgpr_workitem_id 2
		.amdhsa_next_free_vgpr 256
		.amdhsa_next_free_sgpr 101
		.amdhsa_accum_offset 256
		.amdhsa_reserve_vcc 1
		.amdhsa_float_round_mode_32 0
		.amdhsa_float_round_mode_16_64 0
		.amdhsa_float_denorm_mode_32 3
		.amdhsa_float_denorm_mode_16_64 3
		.amdhsa_dx10_clamp 1
		.amdhsa_ieee_mode 1
		.amdhsa_fp16_overflow 0
		.amdhsa_tg_split 0
		.amdhsa_exception_fp_ieee_invalid_op 0
		.amdhsa_exception_fp_denorm_src 0
		.amdhsa_exception_fp_ieee_div_zero 0
		.amdhsa_exception_fp_ieee_overflow 0
		.amdhsa_exception_fp_ieee_underflow 0
		.amdhsa_exception_fp_ieee_inexact 0
		.amdhsa_exception_int_div_zero 0
	.end_amdhsa_kernel

; __global__ void __launch_bounds__(512) fwd_megakernel(Params p) {
amdhsa.kernels:
  - .agpr_count:     0
    .args:
      - .offset:         0
        .size:           152
        .value_kind:     by_value
      - .offset:         152
        .size:           4
        .value_kind:     hidden_block_count_x
      - .offset:         156
        .size:           4
        .value_kind:     hidden_block_count_y
      - .offset:         160
        .size:           4
        .value_kind:     hidden_block_count_z
      - .offset:         164
        .size:           2
        .value_kind:     hidden_group_size_x
      - .offset:         166
        .size:           2
        .value_kind:     hidden_group_size_y
      - .offset:         168
        .size:           2
        .value_kind:     hidden_group_size_z
      - .offset:         170
        .size:           2
        .value_kind:     hidden_remainder_x
      - .offset:         172
        .size:           2
        .value_kind:     hidden_remainder_y
      - .offset:         174
        .size:           2
        .value_kind:     hidden_remainder_z
      - .offset:         192
        .size:           8
        .value_kind:     hidden_global_offset_x
      - .offset:         200
        .size:           8
        .value_kind:     hidden_global_offset_y
      - .offset:         208
        .size:           8
        .value_kind:     hidden_global_offset_z
      - .offset:         216
        .size:           2
        .value_kind:     hidden_grid_dims
      - .offset:         240
        .size:           8
        .value_kind:     hidden_multigrid_sync_arg
      - .offset:         272
        .size:           4
        .value_kind:     hidden_dynamic_lds_size
    .group_segment_fixed_size: 0
    .kernarg_segment_align: 8
    .kernarg_segment_size: 408
    .language:       OpenCL C
    .language_version:
      - 2
      - 0
    .max_flat_workgroup_size: 512
    .name:           _Z14fwd_megakernel6Params
    .private_segment_fixed_size: 0
    .sgpr_count:     107
    .sgpr_spill_count: 198
    .symbol:         _Z14fwd_megakernel6Params.kd
    .uniform_work_group_size: 1
    .uses_dynamic_stack: false
    .vgpr_count:     256
    .vgpr_spill_count: 0
    .wavefront_size: 64
